# E24: E20 + P14 second compress GEMM walks tiles from (blockIdx+128)%256 (4 tiles deep -> 3) + P15 FULL attention tiles skip the hoisted validity compares
# speedup vs baseline: 1.0066x; 1.0066x over previous
.LBB0_4135:
	s_andn2_b64 vcc, exec, s[4:5]
	s_cbranch_vccnz .LBB0_4170
	v_lshlrev_b32_e32 v2, 3, v248
	v_and_b32_e32 v6, 56, v2
	v_lshrrev_b32_e32 v2, 1, v248
	v_and_b32_e32 v82, 0xc0, v2
	v_or_b32_e32 v2, 0x200, v248
	v_readlane_b32 s0, v252, 18
	v_lshrrev_b32_e32 v84, 3, v2
	v_or_b32_e32 v2, 0x600, v248
	v_readlane_b32 s1, v252, 19
	v_readlane_b32 s2, v252, 20
	v_readlane_b32 s3, v252, 21
	s_add_u32 s0, s0, 0x8000
	v_lshrrev_b32_e32 v86, 3, v2
	v_lshlrev_b32_e32 v2, 2, v6
	v_mov_b32_e32 v3, 0
	s_addc_u32 s1, s1, 0
	s_waitcnt vmcnt(0)
	v_lshl_add_u64 v[66:67], s[2:3], 0, v[2:3]
	v_lshlrev_b32_e32 v2, 8, v179
	v_lshl_add_u64 v[4:5], s[0:1], 0, v[2:3]
	v_lshlrev_b32_e32 v2, 1, v6
	v_lshl_add_u64 v[68:69], v[4:5], 0, v[2:3]
	v_lshlrev_b32_e32 v4, 8, v84
	v_mov_b32_e32 v5, v3
	s_waitcnt lgkmcnt(0)
	s_load_dwordx16 s[36:51], s[78:79], 0x1e0
	v_lshl_add_u64 v[4:5], s[0:1], 0, v[4:5]
	v_lshl_add_u64 v[70:71], v[4:5], 0, v[2:3]
	v_mul_u32_u24_e32 v4, 0x90, v179
	v_add3_u32 v87, 0, v4, v2
	v_mul_u32_u24_e32 v4, 0x90, v84
	v_or_b32_e32 v7, v82, v178
	v_and_b32_e32 v8, 0x4f, v248
	v_add3_u32 v88, 0, v4, v2
	v_mul_u32_u24_e32 v4, 0x90, v86
	v_lshlrev_b32_e32 v72, 10, v133
	s_add_u32 s8, s78, 0x2b0
	v_add3_u32 v90, 0, v4, v2
	v_mul_u32_u24_e32 v4, 0x90, v7
	v_mul_u32_u24_e32 v5, 0x90, v8
	v_cmp_ne_u32_e32 vcc, 0, v132
	v_mov_b32_e32 v73, v3
	v_lshl_or_b32 v6, v132, 8, v72
	v_mov_b32_e32 v75, v3
	v_mov_b32_e32 v77, v3
	v_mov_b32_e32 v79, v3
	s_waitcnt lgkmcnt(0)
	v_lshl_add_u64 v[2:3], s[40:41], 0, v[2:3]
	s_mov_b64 s[0:1], 0x2200000
	v_and_b32_e32 v83, 3, v248
	s_addc_u32 s9, s79, 0
	v_or_b32_e32 v85, 0x80, v179
	v_add_u32_e32 v89, 0x4800, v87
	s_movk_i32 s16, 0x1000
	v_or_b32_e32 v74, 0x1000, v6
	v_or_b32_e32 v76, 0x2000, v6
	v_or_b32_e32 v78, 0x3000, v6
	v_lshl_add_u64 v[80:81], v[2:3], 0, s[0:1]
	s_movk_i32 s17, 0x7f
	v_add_u32_e32 v91, v1, v4
	v_add_u32_e32 v1, v1, v5
	s_mov_b32 s18, 0x11000
	s_xor_b64 s[10:11], vcc, -1
	s_movk_i32 s19, 0xfff
	s_movk_i32 s20, 0x7fff
	s_add_i32 s21, s76, 0x80
	s_and_b32 s21, s21, 0xff
	s_branch .LBB0_4140
